# MLP-out B epilogue row-sum cross-lane steps via permlane16/32 swaps as well (all four resid/GLU epilogues now bpermute-free)
# speedup vs baseline: 1.0029x; 1.0029x over previous
.LBB0_1137:
	v_readlane_b32 s28, v255, 11
	v_readlane_b32 s29, v255, 12
	s_lshl_b32 s26, s8, 2
	s_ashr_i32 s27, s26, 31
	v_cndmask_b32_e64 v138, 0, 1, s[28:29]
	v_cmp_ne_u32_e64 s[8:9], 1, v138
	s_andn2_b64 vcc, exec, s[28:29]
	v_xor_b32_e32 v139, 16, v1
	v_and_b32_e32 v140, 64, v1
	v_xor_b32_e32 v138, 32, v1
	s_cbranch_vccnz .LBB0_1141
	v_mul_f32_e32 v114, v114, v114
	v_mul_f32_e32 v126, v126, v126
	v_mul_f32_e32 v122, v122, v122
	v_mul_f32_e32 v118, v118, v118
	v_fmac_f32_e32 v114, v115, v115
	v_mul_f32_e32 v115, v117, v117
	v_fmac_f32_e32 v126, v127, v127
	v_mul_f32_e32 v127, v128, v128
	v_fmac_f32_e32 v122, v123, v123
	v_mul_f32_e32 v123, v125, v125
	v_fmac_f32_e32 v118, v119, v119
	v_mul_f32_e32 v119, v120, v120
	v_fmac_f32_e32 v115, v116, v116
	v_fmac_f32_e32 v127, v129, v129
	v_fmac_f32_e32 v123, v124, v124
	v_fmac_f32_e32 v119, v121, v121
	v_add_f32_e32 v114, v115, v114
	v_add_u32_e32 v115, 64, v140
	v_add_f32_e32 v126, v127, v126
	v_add_f32_e32 v122, v123, v122
	v_add_f32_e32 v118, v119, v118
	v_cmp_lt_i32_e32 vcc, v139, v115
	v_add_f32_e32 v122, v122, v126
	v_add_f32_e32 v114, v114, v118
	v_cndmask_b32_e32 v116, v1, v139, vcc
	v_add_f32_e32 v114, v122, v114
	v_lshlrev_b32_e32 v116, 2, v116
	v_cmp_lt_i32_e32 vcc, v138, v115
	s_nop 0
	v_mov_b32_e32 v116, v114
	v_mov_b32_e32 v190, v114
	s_nop 1
	v_permlane16_swap_b32 v116, v190
	v_add_f32_e32 v114, v116, v190
	v_cndmask_b32_e32 v115, v1, v138, vcc
	v_lshlrev_b32_e32 v115, 2, v115
	v_mov_b32_e32 v115, v114
	v_mov_b32_e32 v190, v114
	s_nop 1
	v_permlane32_swap_b32 v190, v115
	s_and_saveexec_b64 s[28:29], s[0:1]
	s_cbranch_execz .LBB0_1140
	v_lshlrev_b64 v[116:117], 7, v[154:155]
	v_lshl_add_u64 v[116:117], s[10:11], 0, v[116:117]
	v_lshl_add_u64 v[116:117], s[26:27], 2, v[116:117]
	s_lshl_b32 s94, s48, 2
	v_lshl_add_u64 v[116:117], v[116:117], 0, s[94:95]
	s_nop 0
	v_add_f32_e32 v114, v114, v115
	global_store_dword v[116:117], v114, off

.LBB0_1147:
	s_and_b64 vcc, exec, s[8:9]
	s_cbranch_vccnz .LBB0_1151
	v_mul_f32_e32 v98, v98, v98
	v_mul_f32_e32 v110, v110, v110
	v_mul_f32_e32 v106, v106, v106
	v_mul_f32_e32 v102, v102, v102
	v_fmac_f32_e32 v98, v99, v99
	v_mul_f32_e32 v99, v101, v101
	v_fmac_f32_e32 v110, v111, v111
	v_mul_f32_e32 v111, v112, v112
	v_fmac_f32_e32 v106, v107, v107
	v_mul_f32_e32 v107, v109, v109
	v_fmac_f32_e32 v102, v103, v103
	v_mul_f32_e32 v103, v104, v104
	v_fmac_f32_e32 v99, v100, v100
	v_fmac_f32_e32 v111, v113, v113
	v_fmac_f32_e32 v107, v108, v108
	v_fmac_f32_e32 v103, v105, v105
	v_add_f32_e32 v98, v99, v98
	v_add_u32_e32 v99, 64, v140
	v_add_f32_e32 v110, v111, v110
	v_add_f32_e32 v106, v107, v106
	v_add_f32_e32 v102, v103, v102
	v_cmp_lt_i32_e32 vcc, v139, v99
	v_add_f32_e32 v106, v106, v110
	v_add_f32_e32 v98, v98, v102
	v_cndmask_b32_e32 v100, v1, v139, vcc
	v_add_f32_e32 v98, v106, v98
	v_lshlrev_b32_e32 v100, 2, v100
	v_cmp_lt_i32_e32 vcc, v138, v99
	s_nop 0
	v_mov_b32_e32 v100, v98
	v_mov_b32_e32 v190, v98
	s_nop 1
	v_permlane16_swap_b32 v100, v190
	v_add_f32_e32 v98, v100, v190
	v_cndmask_b32_e32 v99, v1, v138, vcc
	v_lshlrev_b32_e32 v99, 2, v99
	v_mov_b32_e32 v99, v98
	v_mov_b32_e32 v190, v98
	s_nop 1
	v_permlane32_swap_b32 v190, v99
	s_and_saveexec_b64 s[28:29], s[0:1]
	s_cbranch_execz .LBB0_1150
	v_lshlrev_b64 v[100:101], 7, v[156:157]
	v_lshl_add_u64 v[100:101], s[10:11], 0, v[100:101]
	v_lshl_add_u64 v[100:101], s[26:27], 2, v[100:101]
	s_lshl_b32 s94, s48, 2
	v_lshl_add_u64 v[100:101], v[100:101], 0, s[94:95]
	s_nop 0
	v_add_f32_e32 v98, v98, v99
	global_store_dword v[100:101], v98, off

.LBB0_1157:
	s_and_b64 vcc, exec, s[8:9]
	s_cbranch_vccnz .LBB0_1161
	v_mul_f32_e32 v82, v82, v82
	v_mul_f32_e32 v94, v94, v94
	v_mul_f32_e32 v90, v90, v90
	v_mul_f32_e32 v86, v86, v86
	v_fmac_f32_e32 v82, v83, v83
	v_mul_f32_e32 v83, v85, v85
	v_fmac_f32_e32 v94, v95, v95
	v_mul_f32_e32 v95, v96, v96
	v_fmac_f32_e32 v90, v91, v91
	v_mul_f32_e32 v91, v93, v93
	v_fmac_f32_e32 v86, v87, v87
	v_mul_f32_e32 v87, v88, v88
	v_fmac_f32_e32 v83, v84, v84
	v_fmac_f32_e32 v95, v97, v97
	v_fmac_f32_e32 v91, v92, v92
	v_fmac_f32_e32 v87, v89, v89
	v_add_f32_e32 v82, v83, v82
	v_add_u32_e32 v83, 64, v140
	v_add_f32_e32 v94, v95, v94
	v_add_f32_e32 v90, v91, v90
	v_add_f32_e32 v86, v87, v86
	v_cmp_lt_i32_e32 vcc, v139, v83
	v_add_f32_e32 v90, v90, v94
	v_add_f32_e32 v82, v82, v86
	v_cndmask_b32_e32 v84, v1, v139, vcc
	v_add_f32_e32 v82, v90, v82
	v_lshlrev_b32_e32 v84, 2, v84
	v_cmp_lt_i32_e32 vcc, v138, v83
	s_nop 0
	v_mov_b32_e32 v84, v82
	v_mov_b32_e32 v190, v82
	s_nop 1
	v_permlane16_swap_b32 v84, v190
	v_add_f32_e32 v82, v84, v190
	v_cndmask_b32_e32 v83, v1, v138, vcc
	v_lshlrev_b32_e32 v83, 2, v83
	v_mov_b32_e32 v83, v82
	v_mov_b32_e32 v190, v82
	s_nop 1
	v_permlane32_swap_b32 v190, v83
	s_and_saveexec_b64 s[28:29], s[0:1]
	s_cbranch_execz .LBB0_1160
	v_lshlrev_b64 v[84:85], 7, v[122:123]
	v_lshl_add_u64 v[84:85], s[10:11], 0, v[84:85]
	v_lshl_add_u64 v[84:85], s[26:27], 2, v[84:85]
	s_lshl_b32 s94, s48, 2
	v_lshl_add_u64 v[84:85], v[84:85], 0, s[94:95]
	s_nop 0
	v_add_f32_e32 v82, v82, v83
	global_store_dword v[84:85], v82, off

.LBB0_1167:
	s_and_b64 vcc, exec, s[8:9]
	s_cbranch_vccnz .LBB0_1171
	v_mul_f32_e32 v66, v66, v66
	v_mul_f32_e32 v78, v78, v78
	v_mul_f32_e32 v74, v74, v74
	v_mul_f32_e32 v70, v70, v70
	v_fmac_f32_e32 v66, v67, v67
	v_mul_f32_e32 v67, v69, v69
	v_fmac_f32_e32 v78, v79, v79
	v_mul_f32_e32 v79, v80, v80
	v_fmac_f32_e32 v74, v75, v75
	v_mul_f32_e32 v75, v77, v77
	v_fmac_f32_e32 v70, v71, v71
	v_mul_f32_e32 v71, v72, v72
	v_fmac_f32_e32 v67, v68, v68
	v_fmac_f32_e32 v79, v81, v81
	v_fmac_f32_e32 v75, v76, v76
	v_fmac_f32_e32 v71, v73, v73
	v_add_f32_e32 v66, v67, v66
	v_add_u32_e32 v67, 64, v140
	v_add_f32_e32 v78, v79, v78
	v_add_f32_e32 v74, v75, v74
	v_add_f32_e32 v70, v71, v70
	v_cmp_lt_i32_e32 vcc, v139, v67
	v_add_f32_e32 v74, v74, v78
	v_add_f32_e32 v66, v66, v70
	v_cndmask_b32_e32 v68, v1, v139, vcc
	v_add_f32_e32 v66, v74, v66
	v_lshlrev_b32_e32 v68, 2, v68
	v_cmp_lt_i32_e32 vcc, v138, v67
	s_nop 0
	v_mov_b32_e32 v68, v66
	v_mov_b32_e32 v190, v66
	s_nop 1
	v_permlane16_swap_b32 v68, v190
	v_add_f32_e32 v66, v68, v190
	v_cndmask_b32_e32 v67, v1, v138, vcc
	v_lshlrev_b32_e32 v67, 2, v67
	v_mov_b32_e32 v67, v66
	v_mov_b32_e32 v190, v66
	s_nop 1
	v_permlane32_swap_b32 v190, v67
	s_and_saveexec_b64 s[28:29], s[0:1]
	s_cbranch_execz .LBB0_1170
	v_lshlrev_b64 v[68:69], 7, v[106:107]
	v_lshl_add_u64 v[68:69], s[10:11], 0, v[68:69]
	v_lshl_add_u64 v[68:69], s[26:27], 2, v[68:69]
	s_lshl_b32 s94, s48, 2
	v_lshl_add_u64 v[68:69], v[68:69], 0, s[94:95]
	s_nop 0
	v_add_f32_e32 v66, v66, v67
	global_store_dword v[68:69], v66, off

.LBB0_1177:
	s_and_b64 vcc, exec, s[8:9]
	s_cbranch_vccnz .LBB0_1181
	v_mul_f32_e32 v50, v50, v50
	v_mul_f32_e32 v62, v62, v62
	v_mul_f32_e32 v58, v58, v58
	v_mul_f32_e32 v54, v54, v54
	v_fmac_f32_e32 v50, v51, v51
	v_mul_f32_e32 v51, v53, v53
	v_fmac_f32_e32 v62, v63, v63
	v_mul_f32_e32 v63, v64, v64
	v_fmac_f32_e32 v58, v59, v59
	v_mul_f32_e32 v59, v61, v61
	v_fmac_f32_e32 v54, v55, v55
	v_mul_f32_e32 v55, v56, v56
	v_fmac_f32_e32 v51, v52, v52
	v_fmac_f32_e32 v63, v65, v65
	v_fmac_f32_e32 v59, v60, v60
	v_fmac_f32_e32 v55, v57, v57
	v_add_f32_e32 v50, v51, v50
	v_add_u32_e32 v51, 64, v140
	v_add_f32_e32 v62, v63, v62
	v_add_f32_e32 v58, v59, v58
	v_add_f32_e32 v54, v55, v54
	v_cmp_lt_i32_e32 vcc, v139, v51
	v_add_f32_e32 v58, v58, v62
	v_add_f32_e32 v50, v50, v54
	v_cndmask_b32_e32 v52, v1, v139, vcc
	v_add_f32_e32 v50, v58, v50
	v_lshlrev_b32_e32 v52, 2, v52
	v_cmp_lt_i32_e32 vcc, v138, v51
	s_nop 0
	v_mov_b32_e32 v52, v50
	v_mov_b32_e32 v190, v50
	s_nop 1
	v_permlane16_swap_b32 v52, v190
	v_add_f32_e32 v50, v52, v190
	v_cndmask_b32_e32 v51, v1, v138, vcc
	v_lshlrev_b32_e32 v51, 2, v51
	v_mov_b32_e32 v51, v50
	v_mov_b32_e32 v190, v50
	s_nop 1
	v_permlane32_swap_b32 v190, v51
	s_and_saveexec_b64 s[28:29], s[0:1]
	s_cbranch_execz .LBB0_1180
	v_lshlrev_b64 v[52:53], 7, v[90:91]
	v_lshl_add_u64 v[52:53], s[10:11], 0, v[52:53]
	v_lshl_add_u64 v[52:53], s[26:27], 2, v[52:53]
	s_lshl_b32 s94, s48, 2
	v_lshl_add_u64 v[52:53], v[52:53], 0, s[94:95]
	s_nop 0
	v_add_f32_e32 v50, v50, v51
	global_store_dword v[52:53], v50, off

.LBB0_1187:
	s_and_b64 vcc, exec, s[8:9]
	s_cbranch_vccnz .LBB0_1191
	v_mul_f32_e32 v34, v34, v34
	v_mul_f32_e32 v46, v46, v46
	v_mul_f32_e32 v42, v42, v42
	v_mul_f32_e32 v38, v38, v38
	v_fmac_f32_e32 v34, v35, v35
	v_mul_f32_e32 v35, v37, v37
	v_fmac_f32_e32 v46, v47, v47
	v_mul_f32_e32 v47, v48, v48
	v_fmac_f32_e32 v42, v43, v43
	v_mul_f32_e32 v43, v45, v45
	v_fmac_f32_e32 v38, v39, v39
	v_mul_f32_e32 v39, v40, v40
	v_fmac_f32_e32 v35, v36, v36
	v_fmac_f32_e32 v47, v49, v49
	v_fmac_f32_e32 v43, v44, v44
	v_fmac_f32_e32 v39, v41, v41
	v_add_f32_e32 v34, v35, v34
	v_add_u32_e32 v35, 64, v140
	v_add_f32_e32 v46, v47, v46
	v_add_f32_e32 v42, v43, v42
	v_add_f32_e32 v38, v39, v38
	v_cmp_lt_i32_e32 vcc, v139, v35
	v_add_f32_e32 v42, v42, v46
	v_add_f32_e32 v34, v34, v38
	v_cndmask_b32_e32 v36, v1, v139, vcc
	v_add_f32_e32 v34, v42, v34
	v_lshlrev_b32_e32 v36, 2, v36
	v_cmp_lt_i32_e32 vcc, v138, v35
	s_nop 0
	v_mov_b32_e32 v36, v34
	v_mov_b32_e32 v190, v34
	s_nop 1
	v_permlane16_swap_b32 v36, v190
	v_add_f32_e32 v34, v36, v190
	v_cndmask_b32_e32 v35, v1, v138, vcc
	v_lshlrev_b32_e32 v35, 2, v35
	v_mov_b32_e32 v35, v34
	v_mov_b32_e32 v190, v34
	s_nop 1
	v_permlane32_swap_b32 v190, v35
	s_and_saveexec_b64 s[28:29], s[0:1]
	s_cbranch_execz .LBB0_1190
	v_lshlrev_b64 v[36:37], 7, v[60:61]
	v_lshl_add_u64 v[36:37], s[10:11], 0, v[36:37]
	v_lshl_add_u64 v[36:37], s[26:27], 2, v[36:37]
	s_lshl_b32 s94, s48, 2
	v_lshl_add_u64 v[36:37], v[36:37], 0, s[94:95]
	s_nop 0
	v_add_f32_e32 v34, v34, v35
	global_store_dword v[36:37], v34, off

.LBB0_1197:
	s_and_b64 vcc, exec, s[8:9]
	s_cbranch_vccnz .LBB0_1201
	v_mul_f32_e32 v18, v18, v18
	v_mul_f32_e32 v30, v30, v30
	v_mul_f32_e32 v26, v26, v26
	v_mul_f32_e32 v22, v22, v22
	v_fmac_f32_e32 v18, v19, v19
	v_mul_f32_e32 v19, v21, v21
	v_fmac_f32_e32 v30, v31, v31
	v_mul_f32_e32 v31, v32, v32
	v_fmac_f32_e32 v26, v27, v27
	v_mul_f32_e32 v27, v29, v29
	v_fmac_f32_e32 v22, v23, v23
	v_mul_f32_e32 v23, v24, v24
	v_fmac_f32_e32 v19, v20, v20
	v_fmac_f32_e32 v31, v33, v33
	v_fmac_f32_e32 v27, v28, v28
	v_fmac_f32_e32 v23, v25, v25
	v_add_f32_e32 v18, v19, v18
	v_add_u32_e32 v19, 64, v140
	v_add_f32_e32 v30, v31, v30
	v_add_f32_e32 v26, v27, v26
	v_add_f32_e32 v22, v23, v22
	v_cmp_lt_i32_e32 vcc, v139, v19
	v_add_f32_e32 v26, v26, v30
	v_add_f32_e32 v18, v18, v22
	v_cndmask_b32_e32 v20, v1, v139, vcc
	v_add_f32_e32 v18, v26, v18
	v_lshlrev_b32_e32 v20, 2, v20
	v_cmp_lt_i32_e32 vcc, v138, v19
	s_nop 0
	v_mov_b32_e32 v20, v18
	v_mov_b32_e32 v190, v18
	s_nop 1
	v_permlane16_swap_b32 v20, v190
	v_add_f32_e32 v18, v20, v190
	v_cndmask_b32_e32 v19, v1, v138, vcc
	v_lshlrev_b32_e32 v19, 2, v19
	v_mov_b32_e32 v19, v18
	v_mov_b32_e32 v190, v18
	s_nop 1
	v_permlane32_swap_b32 v190, v19
	s_and_saveexec_b64 s[28:29], s[0:1]
	s_cbranch_execz .LBB0_1200
	v_lshlrev_b64 v[20:21], 7, v[44:45]
	v_lshl_add_u64 v[20:21], s[10:11], 0, v[20:21]
	v_lshl_add_u64 v[20:21], s[26:27], 2, v[20:21]
	s_lshl_b32 s94, s48, 2
	v_lshl_add_u64 v[20:21], v[20:21], 0, s[94:95]
	s_nop 0
	v_add_f32_e32 v18, v18, v19
	global_store_dword v[20:21], v18, off

.LBB0_1207:
	s_and_b64 vcc, exec, s[8:9]
	s_cbranch_vccnz .LBB0_1122
	v_mul_f32_e32 v2, v2, v2
	v_mul_f32_e32 v14, v14, v14
	v_mul_f32_e32 v10, v10, v10
	v_mul_f32_e32 v6, v6, v6
	v_fmac_f32_e32 v2, v3, v3
	v_mul_f32_e32 v3, v5, v5
	v_fmac_f32_e32 v14, v15, v15
	v_mul_f32_e32 v15, v16, v16
	v_fmac_f32_e32 v10, v11, v11
	v_mul_f32_e32 v11, v13, v13
	v_fmac_f32_e32 v6, v7, v7
	v_mul_f32_e32 v7, v8, v8
	v_fmac_f32_e32 v3, v4, v4
	v_fmac_f32_e32 v15, v17, v17
	v_fmac_f32_e32 v11, v12, v12
	v_fmac_f32_e32 v7, v9, v9
	v_add_f32_e32 v2, v3, v2
	v_add_u32_e32 v3, 64, v140
	v_add_f32_e32 v14, v15, v14
	v_add_f32_e32 v10, v11, v10
	v_add_f32_e32 v6, v7, v6
	v_cmp_lt_i32_e32 vcc, v139, v3
	v_add_f32_e32 v10, v10, v14
	v_add_f32_e32 v2, v2, v6
	v_cndmask_b32_e32 v4, v1, v139, vcc
	v_add_f32_e32 v2, v10, v2
	v_lshlrev_b32_e32 v4, 2, v4
	v_cmp_lt_i32_e32 vcc, v138, v3
	s_nop 0
	v_mov_b32_e32 v4, v2
	v_mov_b32_e32 v190, v2
	s_nop 1
	v_permlane16_swap_b32 v4, v190
	v_add_f32_e32 v2, v4, v190
	v_cndmask_b32_e32 v3, v1, v138, vcc
	v_lshlrev_b32_e32 v3, 2, v3
	v_mov_b32_e32 v3, v2
	v_mov_b32_e32 v190, v2
	s_nop 1
	v_permlane32_swap_b32 v190, v3
	s_and_saveexec_b64 s[6:7], s[0:1]
	s_cbranch_execz .LBB0_1121
	v_lshlrev_b64 v[4:5], 7, v[18:19]
	v_lshl_add_u64 v[4:5], s[10:11], 0, v[4:5]
	v_lshl_add_u64 v[4:5], s[26:27], 2, v[4:5]
	s_lshl_b32 s94, s48, 2
	v_lshl_add_u64 v[4:5], v[4:5], 0, s[94:95]
	s_nop 0
	v_add_f32_e32 v2, v2, v3
	global_store_dword v[4:5], v2, off
	s_branch .LBB0_1121
